# phase 0 hand-out retuned to 24/48 conversion tiles (was 22/52)
# baseline (speedup 1.0000x reference)
; #define TIDX(p) ((p).wv * 64 + (int)__builtin_amdgcn_mbcnt_hi(~0u, __builtin_amdgcn_mbcnt_lo(~0u, 0u)))
; DI void phase0(const PX& p, unsigned char* smem) {
;   float* sm = (float*)smem;
;   if (blockIdx.x == 0 && TIDX(p) < 64) ((unsigned*)(p.ws + OFF_CNT))[TIDX(p)] = 0u;
;   const int n_mod = 384;
;   const int total = n_mod + MIX_TILES + N_FILT_ITEMS;
;   for (int it = blockIdx.x; it < total; it += gridDim.x) {
;     if (it < n_mod) { if (EN & 256) mod_partial(p, it, sm); }
;     else if (it < n_mod + N_FILT_ITEMS) { if (EN & 512) filter_item(p, it - n_mod, sm); }
;     else convert_mixer(p, 0, it - n_mod - N_FILT_ITEMS, sm);
;   }
; }
.LBB0_797:
	s_cmpk_lg_i32 s83, 0x100
	s_cbranch_scc1 .Lp0_orig
	v_readlane_b32 vcc_lo, v255, 63
	s_add_i32 vcc_lo, vcc_lo, 1
	v_writelane_b32 v255, vcc_lo, 63
	v_readlane_b32 vcc_hi, v252, 0
	s_cmp_lt_u32 vcc_lo, 4
	s_cbranch_scc1 .Lp0_early
	s_sub_u32 vcc_lo, vcc_lo, 4
	s_cmp_lt_u32 vcc_hi, 0xa0
	s_cbranch_scc0 .Lp0_light
	s_cmp_ge_u32 vcc_lo, 24
	s_cbranch_scc1 .LBB0_1108
	s_mul_i32 s1, vcc_lo, 0xa0
	s_add_i32 s1, s1, vcc_hi
	s_addk_i32 s1, 0x400
	s_branch .Lp0_chk
.Lp0_light:
	s_cmp_ge_u32 vcc_lo, 48
	s_cbranch_scc1 .LBB0_1108
	s_mul_i32 s1, vcc_lo, 0x60
	s_add_i32 s1, s1, vcc_hi
	s_addk_i32 s1, 0x1260
	s_branch .Lp0_chk
